# v35 + indexer scoring loop key/query loads as global loads (flat loads were saturating lgkmcnt alongside the LDS histogram ops)
# speedup vs baseline: 1.0169x; 1.0041x over previous
; DI float bf2f(bf16_t v) { return __uint_as_float(((unsigned)v) << 16); }
; DI void dsa_index_phase(unsigned char* lds, KParamPtr P, int wv) {
;     ...
;   for (int item = blockIdx.x; item < 8192; item += gridDim.x) {
;     const int b = (item & 7) >> 1, t0 = (((item >> 3) << 1) + (item & 1)) * 4;
;     const int ntile = (t0 + 4 + 31) >> 5;
;     bf16x8 af[4];
;     const bf16_t* iqp = proj + (size_t)(b * SEQ + t0 + ru) * EIN + C_IQ + rhead * 64 + hh * 8;
; #pragma unroll
;     for (int ks = 0; ks < 4; ++ks) af[ks] = ldg8(iqp + ks * 16);
;     float w[16];
; #pragma unroll
;     for (int i = 0; i < 16; ++i) {
;       const int uq = 2 * hh + (i >> 3), hd = (i & 3) + 4 * ((i >> 2) & 1);
;       w[i] = bf2f(proj[(size_t)(b * SEQ + t0 + uq) * EIN + C_IW + hd]) * 0.04419417382415922f;
;     }
; #pragma unroll 1
;     for (int kt0 = wave * 4; kt0 < ntile; kt0 += 32) {
;       bf16x8 kf[4][4];
;       const unsigned ko = (unsigned)((b * SEQ + kt0 * 32 + l31) * EIN + C_IK + hh * 8);
.LBB0_852:
	s_lshl_b32 s2, s35, 2
	s_and_b32 s2, s2, 4
	s_and_b32 s18, s35, -8
	s_or_b32 s24, s2, s18
	s_add_i32 s2, s24, 35
	s_lshl_b32 s18, s35, 12
	s_and_b32 s18, s18, 0x6000
	s_ashr_i32 s26, s2, 5
	s_add_i32 s25, s24, s18
	v_cmp_gt_i32_e32 vcc, s26, v98
	s_and_saveexec_b64 s[18:19], vcc
	s_cbranch_execz .LBB0_871
	v_or_b32_e32 v0, s25, v97
	v_mov_b64_e32 v[6:7], s[84:85]
	s_waitcnt lgkmcnt(0)
	v_mad_i64_i32 v[2:3], s[20:21], v0, s87, v[6:7]
	v_add_co_u32_e32 v2, vcc, 0x1000, v2
	v_or_b32_e32 v0, 1, v0
	s_nop 0
	v_addc_co_u32_e32 v3, vcc, 0, v3, vcc
	v_mad_i64_i32 v[6:7], s[20:21], v0, s87, v[6:7]
	s_movk_i32 s2, 0x1000
	v_add_co_u32_e32 v6, vcc, s2, v6
	v_or_b32_e32 v0, s25, v96
	s_nop 0
	v_addc_co_u32_e32 v7, vcc, 0, v7, vcc
	v_mad_i64_i32 v[10:11], s[20:21], v0, s87, v[92:93]
	global_load_dwordx4 v[2:5], v[2:3], off offset:944
	s_and_b32 s2, s88, 0x6000
	global_load_dwordx4 v[6:9], v[6:7], off offset:944
	s_nop 0
	global_load_dwordx4 v[18:21], v[10:11], off offset:3888
	global_load_dwordx4 v[22:25], v[10:11], off offset:3920
	global_load_dwordx4 v[26:29], v[10:11], off offset:3952
	global_load_dwordx4 v[30:33], v[10:11], off offset:3984
	v_add_u32_e32 v0, s2, v119
	v_lshrrev_b32_e32 v10, 5, v0
	v_lshlrev_b32_e32 v10, 11, v10
	v_and_b32_e32 v11, 31, v0
	v_lshl_or_b32 v10, v11, 4, v10
	v_add_u32_e32 v10, v10, v94
	v_add_u32_e32 v10, 0x8fff668, v10
	v_or_b32_e32 v120, s24, v97
	v_mov_b32_e32 v0, v10
	s_mov_b64 s[20:21], 0
	v_mov_b32_e32 v121, v119
	v_mov_b32_e32 v122, v118
	v_or_b32_e32 v123, 1, v120
	v_mov_b32_e32 v140, v98
	s_waitcnt vmcnt(0) lgkmcnt(0)
	v_lshlrev_b32_e32 v10, 16, v2
	v_and_b32_e32 v2, 0xffff0000, v2
	v_lshlrev_b32_e32 v11, 16, v3
	v_and_b32_e32 v3, 0xffff0000, v3
	v_lshlrev_b32_e32 v12, 16, v4
	v_and_b32_e32 v4, 0xffff0000, v4
	v_lshlrev_b32_e32 v13, 16, v5
	v_and_b32_e32 v5, 0xffff0000, v5
	v_lshlrev_b32_e32 v14, 16, v6
	v_and_b32_e32 v6, 0xffff0000, v6
	v_lshlrev_b32_e32 v15, 16, v7
	v_and_b32_e32 v7, 0xffff0000, v7
	v_lshlrev_b32_e32 v16, 16, v8
	v_and_b32_e32 v8, 0xffff0000, v8
	v_lshlrev_b32_e32 v17, 16, v9
	v_and_b32_e32 v9, 0xffff0000, v9
	v_mul_f32_e32 v124, 0x3d3504f3, v10
	v_mul_f32_e32 v125, 0x3d3504f3, v2
	v_mul_f32_e32 v126, 0x3d3504f3, v11
	v_mul_f32_e32 v127, 0x3d3504f3, v3
	v_mul_f32_e32 v128, 0x3d3504f3, v12
	v_mul_f32_e32 v129, 0x3d3504f3, v4
	v_mul_f32_e32 v130, 0x3d3504f3, v13
	v_mul_f32_e32 v131, 0x3d3504f3, v5
	v_mul_f32_e32 v132, 0x3d3504f3, v14
	v_mul_f32_e32 v133, 0x3d3504f3, v6
	v_mul_f32_e32 v134, 0x3d3504f3, v15
	v_mul_f32_e32 v135, 0x3d3504f3, v7
	v_mul_f32_e32 v136, 0x3d3504f3, v16
	v_mul_f32_e32 v137, 0x3d3504f3, v8
	v_mul_f32_e32 v138, 0x3d3504f3, v17
	v_mul_f32_e32 v139, 0x3d3504f3, v9
	s_branch .LBB0_855

; #define MFMA32(a, b, c) __builtin_amdgcn_mfma_f32_32x32x16_bf16((a), (b), (c), 0, 0, 0)
; DI unsigned fkey(float f) { unsigned u = __float_as_uint(f); return (u & 0x80000000u) ? ~u : (u | 0x80000000u); }
; DI void dsa_index_phase(unsigned char* lds, KParamPtr P, int wv) {
;     ...
;     for (int kt0 = wave * 4; kt0 < ntile; kt0 += 32) {
;       bf16x8 kf[4][4];
;       const unsigned ko = (unsigned)((b * SEQ + kt0 * 32 + l31) * EIN + C_IK + hh * 8);
; #pragma unroll
;       for (int u = 0; u < 4; ++u)
; #pragma unroll
;         for (int ks = 0; ks < 4; ++ks) kf[u][ks] = ldg8(proj + ko + (unsigned)(u * 32 * EIN + ks * 16));
; #pragma unroll
;       for (int u = 0; u < 4; ++u) {
;         f32x16 acc = zero16();
; #pragma unroll
;         for (int ks = 0; ks < 4; ++ks) acc = MFMA32(af[ks], kf[u][ks], acc);
;         float s0 = 0.f, s1 = 0.f;
; #pragma unroll
;         for (int i = 0; i < 8; ++i) { s0 += w[i] * fmaxf(acc[i], 0.f); s1 += w[8 + i] * fmaxf(acc[8 + i], 0.f); }
;         const int key = (kt0 + u) * 32 + l31;
;         s0 += 0.f; s1 += 0.f;
;         sc[(2 * hh) * 8192 + key] = s0;
;         sc[(2 * hh + 1) * 8192 + key] = s1;
;         if (key <= t0 + 2 * hh) atomicAdd(hist + (2 * hh) * 256 + (fkey(s0) >> 24), 1u);
;         if (key <= t0 + 2 * hh + 1) atomicAdd(hist + (2 * hh + 1) * 256 + (fkey(s1) >> 24), 1u);
.LBB0_855:
	v_lshl_add_u64 v[38:39], v[0:1], 1, s[84:85]
	global_load_dwordx4 v[2:5], v[38:39], off
	global_load_dwordx4 v[34:37], v[38:39], off offset:1024
	global_load_dwordx4 v[42:45], v[38:39], off offset:2048
	global_load_dwordx4 v[142:145], v[38:39], off offset:3072
	v_add_co_u32_e32 v6, vcc, 0x1000, v38
	s_mov_b32 s2, 0x2000
	s_nop 0
	v_addc_co_u32_e32 v7, vcc, 0, v39, vcc
	global_load_dwordx4 v[78:81], v[6:7], off
	global_load_dwordx4 v[74:77], v[6:7], off offset:1024
	global_load_dwordx4 v[70:73], v[6:7], off offset:2048
	global_load_dwordx4 v[66:69], v[6:7], off offset:3072
	v_add_co_u32_e32 v40, vcc, s2, v38
	s_mov_b32 s2, 0x3000
	s_nop 0
	v_addc_co_u32_e32 v41, vcc, 0, v39, vcc
	v_add_co_u32_e32 v46, vcc, s2, v38
	global_load_dwordx4 v[62:65], v[40:41], off
	global_load_dwordx4 v[54:57], v[40:41], off offset:1024
	v_addc_co_u32_e32 v47, vcc, 0, v39, vcc
	global_load_dwordx4 v[58:61], v[40:41], off offset:2048
	global_load_dwordx4 v[50:53], v[40:41], off offset:3072
	v_cmp_le_i32_e32 vcc, v121, v120
	s_waitcnt vmcnt(0) lgkmcnt(0)
	v_mfma_f32_32x32x16_bf16 v[2:17], v[18:21], v[2:5], 0
	v_mfma_f32_32x32x16_bf16 v[2:17], v[22:25], v[34:37], v[2:17]
	global_load_dwordx4 v[38:41], v[46:47], off
	global_load_dwordx4 v[34:37], v[46:47], off offset:1024
	v_mfma_f32_32x32x16_bf16 v[2:17], v[26:29], v[42:45], v[2:17]
	global_load_dwordx4 v[42:45], v[46:47], off offset:2048
	s_nop 0
	global_load_dwordx4 v[46:49], v[46:47], off offset:3072
	v_mfma_f32_32x32x16_bf16 v[2:17], v[30:33], v[142:145], v[2:17]
	s_nop 11
	v_max_f32_e32 v2, v2, v2
	v_max_f32_e32 v10, v10, v10
	v_max_f32_e32 v3, v3, v3
	v_max_f32_e32 v11, v11, v11
	v_max_f32_e32 v2, 0, v2
	v_max_f32_e32 v10, 0, v10
	v_max_f32_e32 v4, v4, v4
	v_max_f32_e32 v12, v12, v12
	v_max_f32_e32 v3, 0, v3
	v_max_f32_e32 v11, 0, v11
	v_fma_f32 v2, v124, v2, 0
	v_fma_f32 v10, v132, v10, 0
	v_max_f32_e32 v5, v5, v5
	v_max_f32_e32 v13, v13, v13
	v_max_f32_e32 v4, 0, v4
	v_max_f32_e32 v12, 0, v12
	v_fmac_f32_e32 v2, v125, v3
	v_fmac_f32_e32 v10, v133, v11
	v_max_f32_e32 v6, v6, v6
	v_max_f32_e32 v14, v14, v14
	v_max_f32_e32 v5, 0, v5
	v_max_f32_e32 v13, 0, v13
	v_fmac_f32_e32 v2, v126, v4
	v_fmac_f32_e32 v10, v134, v12
	v_max_f32_e32 v7, v7, v7
	v_max_f32_e32 v15, v15, v15
	v_max_f32_e32 v6, 0, v6
	v_max_f32_e32 v14, 0, v14
	v_fmac_f32_e32 v2, v127, v5
	v_fmac_f32_e32 v10, v135, v13
	v_max_f32_e32 v8, v8, v8
	v_max_f32_e32 v16, v16, v16
	v_max_f32_e32 v7, 0, v7
	v_max_f32_e32 v15, 0, v15
	v_fmac_f32_e32 v2, v128, v6
	v_fmac_f32_e32 v10, v136, v14
	v_max_f32_e32 v9, v9, v9
	v_max_f32_e32 v17, v17, v17
	v_max_f32_e32 v8, 0, v8
	v_max_f32_e32 v16, 0, v16
	v_fmac_f32_e32 v2, v129, v7
	v_fmac_f32_e32 v10, v137, v15
	v_max_f32_e32 v9, 0, v9
	v_max_f32_e32 v17, 0, v17
	v_fmac_f32_e32 v2, v130, v8
	v_fmac_f32_e32 v10, v138, v16
	v_fmac_f32_e32 v2, v131, v9
	v_fmac_f32_e32 v10, v139, v17
	v_add_f32_e32 v3, 0, v2
	v_add_f32_e32 v2, 0, v10
	ds_write2st64_b32 v122, v3, v2 offset1:128
	s_and_saveexec_b64 s[22:23], vcc
	s_cbranch_execz .LBB0_857
	v_not_b32_e32 v4, v3
	v_or_b32_e32 v5, 0x80000000, v3
	v_cmp_gt_i32_e32 vcc, 0, v3
	s_nop 1
	v_cndmask_b32_e32 v3, v5, v4, vcc
	v_lshrrev_b32_e32 v3, 24, v3
	v_lshl_add_u32 v3, v3, 2, v99
	ds_add_u32 v3, v214
